# v1 plus: last 528 weight-conversion items moved to the 7-unit workgroups
# speedup vs baseline: 1.0008x; 1.0008x over previous
.LBB0_306:
	s_cmp_gt_i32 s78, 15
	s_cbranch_scc1 .LBB0_403
	v_readlane_b32 s12, v244, 39
	v_ashrrev_i32_e32 v111, 6, v1
	v_mov_b32_e32 v1, v220
	s_add_i32 s16, s12, 1
	s_movk_i32 s12, 0x4200
	v_and_b32_e32 v69, 63, v1
	v_mul_lo_u32 v1, v111, s12
	v_readlane_b32 s18, v245, 59
	v_add_u32_e32 v1, 0, v1
	s_and_b64 vcc, exec, s[38:39]
	v_readlane_b32 s19, v245, 60
	v_readlane_b32 s13, v244, 40
	s_cbranch_vccnz .LBB0_357
	v_readlane_b32 s12, v245, 63
	v_readlane_b32 s13, v244, 0
	s_mov_b64 s[18:19], -1
	s_and_b64 vcc, exec, s[12:13]
	s_cbranch_vccz .LBB0_357
	v_readlane_b32 s12, v244, 1
	v_readlane_b32 s13, v244, 2
	v_readlane_b32 s12, v244, 10
	s_movk_i32 s100, 0x1fff
	s_cmp_lt_i32 s12, 0
	s_cbranch_scc0 .Lcv_six
	s_addk_i32 s12, 0x2400
	s_movk_i32 s100, 0x220f
.Lcv_six:
	v_add_u32_e32 v113, s12, v111
	v_cmp_ge_i32_e32 vcc, s100, v113
	s_and_saveexec_b64 s[18:19], vcc
	s_cbranch_execz .LBB0_355
	s_ashr_i32 s17, s16, 31
	v_readlane_b32 s20, v246, 0
	s_lshl_b64 s[12:13], s[16:17], 25
	v_readlane_b32 s22, v246, 2
	v_readlane_b32 s21, v246, 1
	v_readlane_b32 s23, v246, 3
	s_add_u32 s12, s22, s12
	s_addc_u32 s13, s23, s13
	s_lshl_b64 s[20:21], s[16:17], 24
	v_lshlrev_b32_e32 v2, 4, v69
	s_add_u32 s20, s6, s20
	v_and_b32_e32 v2, 0x70, v2
	v_mov_b32_e32 v3, v0
	s_addc_u32 s21, s7, s21
	v_lshl_add_u64 v[66:67], s[12:13], 0, v[2:3]
	s_lshl_b64 s[12:13], s[16:17], 17
	s_add_u32 s40, s83, s12
	v_readlane_b32 s12, v246, 23
	s_addc_u32 s41, s12, s13
	s_lshl_b32 s12, s16, 11
	s_ashr_i32 s13, s12, 31
	s_lshl_b64 s[12:13], s[12:13], 2
	s_add_u32 s42, s54, s12
	v_lshlrev_b32_e32 v4, 3, v69
	s_addc_u32 s43, s55, s13
	s_mul_i32 s12, s16, 0x6840000
	v_lshrrev_b32_e32 v9, 4, v69
	v_and_b32_e32 v68, 0x78, v4
	s_mul_hi_i32 s13, s16, 0x6840000
	s_add_u32 s12, s56, s12
	v_lshrrev_b32_e32 v115, 3, v69
	v_mul_u32_u24_e32 v4, 0x84, v68
	v_lshlrev_b32_e32 v6, 2, v9
	v_or_b32_e32 v11, 4, v9
	v_or_b32_e32 v13, 8, v9
	v_or_b32_e32 v15, 12, v9
	v_or_b32_e32 v17, 16, v9
	v_or_b32_e32 v19, 20, v9
	v_or_b32_e32 v21, 24, v9
	v_or_b32_e32 v23, 28, v9
	s_addc_u32 s13, s57, s13
	v_readlane_b32 s26, v246, 6
	v_add_u32_e32 v5, v1, v2
	v_mul_u32_u24_e32 v7, 0x84, v115
	v_add3_u32 v119, v1, v4, v6
	v_lshlrev_b32_e32 v4, 12, v9
	v_lshlrev_b32_e32 v6, 12, v11
	v_lshlrev_b32_e32 v8, 12, v13
	v_lshlrev_b32_e32 v10, 12, v15
	v_lshlrev_b32_e32 v12, 12, v17
	v_lshlrev_b32_e32 v14, 12, v19
	v_lshlrev_b32_e32 v16, 12, v21
	v_lshlrev_b32_e32 v18, 12, v23
	v_lshlrev_b32_e32 v20, 11, v9
	v_lshlrev_b32_e32 v22, 11, v11
	v_lshlrev_b32_e32 v24, 11, v13
	v_lshlrev_b32_e32 v26, 11, v15
	v_lshlrev_b32_e32 v28, 11, v17
	v_lshlrev_b32_e32 v30, 11, v19
	v_lshlrev_b32_e32 v32, 11, v21
	v_lshlrev_b32_e32 v34, 11, v23
	v_lshl_add_u64 v[70:71], s[12:13], 0, v[2:3]
	v_readlane_b32 s12, v244, 12
	s_mul_hi_i32 s23, s16, 0x3400
	s_mul_i32 s22, s16, 0x3400
	v_lshlrev_b32_e32 v121, 5, v113
	s_lshl_b32 s17, s12, 5
	v_lshl_add_u32 v123, v113, 1, v230
	s_lshl_b32 s26, s12, 1
	s_mov_b64 s[44:45], 0
	v_lshlrev_b32_e32 v72, 1, v4
	v_lshlrev_b32_e32 v74, 1, v6
	v_lshlrev_b32_e32 v76, 1, v8
	v_lshlrev_b32_e32 v78, 1, v10
	v_lshlrev_b32_e32 v80, 1, v12
	v_lshlrev_b32_e32 v82, 1, v14
	v_lshlrev_b32_e32 v84, 1, v16
	v_lshlrev_b32_e32 v86, 1, v18
	v_lshlrev_b32_e32 v88, 1, v20
	v_lshlrev_b32_e32 v90, 1, v22
	v_lshlrev_b32_e32 v92, 1, v24
	v_lshlrev_b32_e32 v94, 1, v26
	v_lshlrev_b32_e32 v96, 1, v28
	v_lshlrev_b32_e32 v98, 1, v30
	v_lshlrev_b32_e32 v100, 1, v32
	v_lshlrev_b32_e32 v102, 1, v34
	v_add_u32_e32 v125, v5, v7
	v_readlane_b32 s24, v246, 4
	v_readlane_b32 s25, v246, 5
	v_readlane_b32 s27, v246, 7
	s_branch .LBB0_314

.LBB0_313:
	s_or_b64 exec, exec, s[46:47]
	v_readlane_b32 s12, v244, 12
	v_add_u32_e32 v121, s17, v121
	v_add_u32_e32 v123, s26, v123
	v_add_u32_e32 v113, s12, v113
	v_cmp_lt_i32_e32 vcc, s100, v113
	s_or_b64 s[44:45], vcc, s[44:45]
	s_andn2_b64 exec, exec, s[44:45]
	s_cbranch_execz .LBB0_355
